# mixer_out: 56 LDS waits left over from the ds_bpermute form (now before DPP adds) neutralised
# speedup vs baseline: 1.0148x; 1.0019x over previous
; #define LAS __attribute__((address_space(3)))
; __device__ __forceinline__ float bf2f(bf16_t b) { return __uint_as_float((unsigned)b << 16); }
; __device__ __forceinline__ bf16_t f2bf(float f) { return (bf16_t)(pk2(f, 0.f) & 0xffffu); }
; __device__ __forceinline__ float silu_acc(float x) { return x * frcp(1.0f + fexp(-x)); }
; __device__ __forceinline__ void mixer_out_phase(const Ctx& X, LAS unsigned char* lds, int layer, int tid, int wave, int lane) {
;     ...
; #pragma unroll
;             for (int j = 0; j < 4; ++j) {
;                 float sm = (acc[0][j] + acc[1][j]) + (acc[2][j] + acc[3][j]);
;                 sm += __shfl_xor(sm, 1); sm += __shfl_xor(sm, 2); sm += __shfl_xor(sm, 4); sm += __shfl_xor(sm, 8);
;                 const float mu = mixer == 0 ? sm * (1.f / 64.f) : 0.f;
;                 float d[4], s2 = 0.f;
; #pragma unroll
;                 for (int ct = 0; ct < 4; ++ct) { d[ct] = acc[ct][j] - mu; s2 += d[ct] * d[ct]; }
;                 s2 += __shfl_xor(s2, 1); s2 += __shfl_xor(s2, 2); s2 += __shfl_xor(s2, 4); s2 += __shfl_xor(s2, 8);
;                 const float rs = rsqrtf(s2 * (1.f / 64.f) + (mixer == 0 ? 1e-5f : 1e-6f));
;                 const int ii = 16 * (2 * half + rt) + 4 * q + j;
; #pragma unroll
;                 for (int ct = 0; ct < 4; ++ct) { LAS bf16_t* gp = GT + ii * GP + h * 64 + 16 * ct + r;
;                     const float y = d[ct] * rs * wv[ct] * silu_acc(bf2f(*gp));
;                     *gp = on ? f2bf(y) : (bf16_t)0; }
.LpfO_done:
	v_mul_f32_e32 v58, v99, v58
	s_waitcnt lgkmcnt(0)
	v_lshlrev_b32_e32 v62, 16, v62
	v_mul_f32_e32 v66, 0xbfb8aa3b, v62
	v_exp_f32_e32 v66, v66
	s_nop 0
	v_add_f32_e32 v66, 1.0, v66
	v_rcp_f32_e32 v66, v66
	s_nop 0
	v_mul_f32_e32 v62, v66, v62
	v_mul_f32_e32 v58, v62, v58
	v_cvt_pk_bf16_f32 v58, v58, v157
	ds_write_b16 v54, v58 offset:96
	v_mov_b32_e32 v58, v55
	v_mov_b32_e32 v66, v63
	v_pk_add_f32 v[70:71], v[58:59], v[66:67]
	s_nop 0
	v_add_f32_e32 v58, v70, v71
	s_nop 1
	s_nop 0
	v_add_f32_dpp v58, v58, v58 quad_perm:[1,0,3,2] row_mask:0xf bank_mask:0xf
	s_nop 1
	s_nop 0
	v_add_f32_dpp v58, v58, v58 quad_perm:[2,3,0,1] row_mask:0xf bank_mask:0xf
	s_nop 1
	s_nop 0
	v_add_f32_dpp v58, v58, v58 row_half_mirror row_mask:0xf bank_mask:0xf
	s_nop 1
	s_nop 0
	v_add_f32_dpp v58, v58, v58 row_mirror row_mask:0xf bank_mask:0xf
	v_mul_f32_e32 v58, 0x3c800000, v58
	v_cndmask_b32_e32 v66, 0, v58, vcc
	v_mov_b32_e32 v62, v55
	v_pk_add_f32 v[62:63], v[62:63], v[66:67] op_sel_hi:[1,0] neg_lo:[0,1] neg_hi:[0,1]
	v_mov_b32_e32 v58, v67
	v_pk_mul_f32 v[70:71], v[62:63], v[62:63]
	v_pk_add_f32 v[58:59], v[58:59], v[66:67] op_sel_hi:[1,0] neg_lo:[0,1] neg_hi:[0,1]
	v_add_f32_e32 v55, v70, v71
	v_pk_mul_f32 v[66:67], v[58:59], v[58:59]
	v_mov_b32_e32 v70, v68
	v_add_f32_e32 v55, v67, v55
	v_add_f32_e32 v55, v66, v55
	s_nop 1
	v_mov_b32_e32 v71, v60
	s_nop 0
	v_add_f32_dpp v55, v55, v55 quad_perm:[1,0,3,2] row_mask:0xf bank_mask:0xf
	s_nop 1
	s_nop 0
	v_add_f32_dpp v55, v55, v55 quad_perm:[2,3,0,1] row_mask:0xf bank_mask:0xf
	s_nop 1
	s_nop 0
	v_add_f32_dpp v55, v55, v55 row_half_mirror row_mask:0xf bank_mask:0xf
	s_nop 1
	s_nop 0
	v_add_f32_dpp v55, v55, v55 row_mirror row_mask:0xf bank_mask:0xf
	v_fmamk_f32 v55, v55, 0x3c800000, v107
	v_cmp_gt_f32_e64 s[0:1], s3, v55
	v_mul_f32_e32 v66, 0x4b800000, v55
	s_nop 0
	v_cndmask_b32_e64 v55, v55, v66, s[0:1]
	v_rsq_f32_e32 v55, v55
	s_nop 0
	v_mul_f32_e32 v66, 0x45800000, v55
	v_cndmask_b32_e64 v55, v55, v66, s[0:1]
	v_mov_b32_e32 v66, v138
	s_nop 0
	v_mul_f32_e32 v62, v62, v55
	v_mul_f32_e32 v62, v106, v62
	v_mul_f32_e32 v63, v63, v55
	v_mul_f32_e32 v63, v103, v63
	s_nop 0
	v_lshlrev_b32_e32 v66, 16, v66
	v_mul_f32_e32 v67, 0xbfb8aa3b, v66
	v_exp_f32_e32 v67, v67
	v_mul_f32_e32 v59, v59, v55
	v_mul_f32_e32 v59, v101, v59
	v_mul_f32_e32 v55, v58, v55
	v_add_f32_e32 v67, 1.0, v67
	v_rcp_f32_e32 v67, v67
	v_mul_f32_e32 v55, v99, v55
	v_mov_b32_e32 v58, v56
	v_mul_f32_e32 v66, v67, v66
	v_mul_f32_e32 v62, v66, v62
	v_cvt_pk_bf16_f32 v62, v62, v157
	ds_write_b16 v54, v62 offset:528
	v_mov_b32_e32 v62, v139
	s_nop 0
	s_nop 0
	v_lshlrev_b32_e32 v62, 16, v62
	v_mul_f32_e32 v66, 0xbfb8aa3b, v62
	v_exp_f32_e32 v66, v66
	s_nop 0
	v_add_f32_e32 v66, 1.0, v66
	v_rcp_f32_e32 v66, v66
	s_nop 0
	v_mul_f32_e32 v62, v66, v62
	v_mul_f32_e32 v62, v62, v63
	v_cvt_pk_bf16_f32 v62, v62, v157
	ds_write_b16 v54, v62 offset:560
	v_mov_b32_e32 v62, v140
	s_nop 0
	s_nop 0
	v_lshlrev_b32_e32 v62, 16, v62
	v_mul_f32_e32 v63, 0xbfb8aa3b, v62
	v_exp_f32_e32 v63, v63
	s_nop 0
	v_add_f32_e32 v63, 1.0, v63
	v_rcp_f32_e32 v63, v63
	s_nop 0
	v_mul_f32_e32 v62, v63, v62
	v_mul_f32_e32 v59, v62, v59
	v_cvt_pk_bf16_f32 v59, v59, v157
	ds_write_b16 v54, v59 offset:592
	v_mov_b32_e32 v59, v141
	s_nop 0
	v_mov_b32_e32 v63, v68
	v_mov_b32_e32 v68, v65
	s_nop 0
	v_lshlrev_b32_e32 v59, 16, v59
	v_mul_f32_e32 v62, 0xbfb8aa3b, v59
	v_exp_f32_e32 v62, v62
	s_nop 0
	v_add_f32_e32 v62, 1.0, v62
	v_rcp_f32_e32 v62, v62
	s_nop 0
	v_mul_f32_e32 v59, v62, v59
	v_mul_f32_e32 v55, v55, v59
	v_mov_b32_e32 v59, v60
	v_mov_b32_e32 v62, v64
	v_cvt_pk_bf16_f32 v55, v55, v157
	v_pk_add_f32 v[58:59], v[58:59], v[62:63]
	ds_write_b16 v54, v55 offset:624
	v_add_f32_e32 v55, v58, v59
	s_nop 1
	v_mov_b32_e32 v62, v56
	v_mov_b32_e32 v63, v64
	v_mov_b32_e32 v64, v57
	s_nop 0
	v_add_f32_dpp v55, v55, v55 quad_perm:[1,0,3,2] row_mask:0xf bank_mask:0xf
	s_nop 1
	s_nop 0
	v_add_f32_dpp v55, v55, v55 quad_perm:[2,3,0,1] row_mask:0xf bank_mask:0xf
	s_nop 1
	s_nop 0
	v_add_f32_dpp v55, v55, v55 row_half_mirror row_mask:0xf bank_mask:0xf
	s_nop 1
	s_nop 0
	v_add_f32_dpp v55, v55, v55 row_mirror row_mask:0xf bank_mask:0xf
	v_mul_f32_e32 v55, 0x3c800000, v55
	v_cndmask_b32_e32 v58, 0, v55, vcc
	v_pk_add_f32 v[62:63], v[62:63], v[58:59] op_sel_hi:[1,0] neg_lo:[0,1] neg_hi:[0,1]
	v_pk_add_f32 v[58:59], v[70:71], v[58:59] op_sel_hi:[1,0] neg_lo:[0,1] neg_hi:[0,1]
	v_pk_mul_f32 v[66:67], v[62:63], v[62:63]
	v_pk_mul_f32 v[70:71], v[58:59], v[58:59]
	v_add_f32_e32 v55, v66, v67
	v_add_f32_e32 v55, v71, v55
	v_add_f32_e32 v55, v70, v55
	s_nop 1
	v_lshlrev_b32_e32 v66, 16, v17
	v_and_b32_e32 v67, 0xffff0000, v17
	s_nop 0
	v_add_f32_dpp v55, v55, v55 quad_perm:[1,0,3,2] row_mask:0xf bank_mask:0xf
	s_nop 1
	s_nop 0
	v_add_f32_dpp v55, v55, v55 quad_perm:[2,3,0,1] row_mask:0xf bank_mask:0xf
	s_nop 1
	s_nop 0
	v_add_f32_dpp v55, v55, v55 row_half_mirror row_mask:0xf bank_mask:0xf
	s_nop 1
	s_nop 0
	v_add_f32_dpp v55, v55, v55 row_mirror row_mask:0xf bank_mask:0xf
	v_fmamk_f32 v55, v55, 0x3c800000, v107
	v_cmp_gt_f32_e64 s[0:1], s3, v55
	v_mul_f32_e32 v56, 0x4b800000, v55
	s_nop 0
	v_cndmask_b32_e64 v55, v55, v56, s[0:1]
	v_rsq_f32_e32 v55, v55
	s_nop 0
	v_mul_f32_e32 v56, 0x45800000, v55
	v_cndmask_b32_e64 v55, v55, v56, s[0:1]
	v_mov_b32_e32 v56, v142
	s_nop 0
	v_mul_f32_e32 v59, v59, v55
	v_mul_f32_e32 v59, v101, v59
	s_nop 0
	v_lshlrev_b32_e32 v56, 16, v56
	v_mul_f32_e32 v60, 0xbfb8aa3b, v56
	v_exp_f32_e32 v60, v60
	s_nop 0
	v_add_f32_e32 v60, 1.0, v60
	v_rcp_f32_e32 v60, v60
	s_nop 0
	v_mul_f32_e32 v56, v60, v56
	v_mul_f32_e32 v60, v62, v55
	v_mul_f32_e32 v60, v106, v60
; #define LAS __attribute__((address_space(3)))
; __device__ __forceinline__ float bf_lo(unsigned u) { return __uint_as_float(u << 16); }
; __device__ __forceinline__ float bf_hi(unsigned u) { return __uint_as_float(u & 0xffff0000u); }
; __device__ __forceinline__ float bf2f(bf16_t b) { return __uint_as_float((unsigned)b << 16); }
; __device__ __forceinline__ bf16_t f2bf(float f) { return (bf16_t)(pk2(f, 0.f) & 0xffffu); }
; __device__ __forceinline__ float silu_acc(float x) { return x * frcp(1.0f + fexp(-x)); }
; __device__ __forceinline__ void mixer_out_phase(const Ctx& X, LAS unsigned char* lds, int layer, int tid, int wave, int lane) {
;     ...
;         for (int rt = 0; rt < 2; ++rt) {
;             f32x4 acc[4];
;             acc[0] = (f32x4){bf_lo(ov[rt][0].x), bf_hi(ov[rt][0].x), bf_lo(ov[rt][0].y), bf_hi(ov[rt][0].y)}; acc[1] = (f32x4){bf_lo(ov[rt][0].z), bf_hi(ov[rt][0].z), bf_lo(ov[rt][0].w), bf_hi(ov[rt][0].w)};
;             acc[2] = (f32x4){bf_lo(ov[rt][1].x), bf_hi(ov[rt][1].x), bf_lo(ov[rt][1].y), bf_hi(ov[rt][1].y)}; acc[3] = (f32x4){bf_lo(ov[rt][1].z), bf_hi(ov[rt][1].z), bf_lo(ov[rt][1].w), bf_hi(ov[rt][1].w)};
; #pragma unroll
;             for (int ct = 0; ct < 4; ++ct)
; #pragma unroll
;                 for (int ks = 0; ks < 2; ++ks) acc[ct] = __builtin_amdgcn_mfma_f32_16x16x32_bf16(a[rt][ks], bb[ct][ks], acc[ct], 0, 0, 0);
; #pragma unroll
;             for (int j = 0; j < 4; ++j) {
;                 float sm = (acc[0][j] + acc[1][j]) + (acc[2][j] + acc[3][j]);
;                 sm += __shfl_xor(sm, 1); sm += __shfl_xor(sm, 2); sm += __shfl_xor(sm, 4); sm += __shfl_xor(sm, 8);
;                 const float mu = mixer == 0 ? sm * (1.f / 64.f) : 0.f;
;                 float d[4], s2 = 0.f;
; #pragma unroll
;                 for (int ct = 0; ct < 4; ++ct) { d[ct] = acc[ct][j] - mu; s2 += d[ct] * d[ct]; }
;                 s2 += __shfl_xor(s2, 1); s2 += __shfl_xor(s2, 2); s2 += __shfl_xor(s2, 4); s2 += __shfl_xor(s2, 8);
;                 const float rs = rsqrtf(s2 * (1.f / 64.f) + (mixer == 0 ? 1e-5f : 1e-6f));
;                 const int ii = 16 * (2 * half + rt) + 4 * q + j;
; #pragma unroll
;                 for (int ct = 0; ct < 4; ++ct) { LAS bf16_t* gp = GT + ii * GP + h * 64 + 16 * ct + r;
;                     const float y = d[ct] * rs * wv[ct] * silu_acc(bf2f(*gp));
;                     *gp = on ? f2bf(y) : (bf16_t)0; }
	v_mul_f32_e32 v56, v56, v60
	v_cvt_pk_bf16_f32 v56, v56, v157
	ds_write_b16 v54, v56 offset:1056
	v_mov_b32_e32 v56, v143
	s_nop 0
	s_nop 0
	v_lshlrev_b32_e32 v56, 16, v56
	v_mul_f32_e32 v60, 0xbfb8aa3b, v56
	v_exp_f32_e32 v60, v60
	s_nop 0
	v_add_f32_e32 v60, 1.0, v60
	v_rcp_f32_e32 v60, v60
	s_nop 0
	v_mul_f32_e32 v56, v60, v56
	v_mul_f32_e32 v60, v63, v55
	v_mul_f32_e32 v60, v103, v60
	v_mul_f32_e32 v56, v56, v60
	v_cvt_pk_bf16_f32 v56, v56, v157
	ds_write_b16 v54, v56 offset:1088
	v_mov_b32_e32 v56, v144
	s_nop 0
	v_mul_f32_e32 v55, v58, v55
	v_mul_f32_e32 v55, v99, v55
	s_nop 0
	v_lshlrev_b32_e32 v56, 16, v56
	v_mul_f32_e32 v60, 0xbfb8aa3b, v56
	v_exp_f32_e32 v60, v60
	s_nop 0
	v_add_f32_e32 v60, 1.0, v60
	v_rcp_f32_e32 v60, v60
	s_nop 0
	v_mul_f32_e32 v56, v60, v56
	v_mul_f32_e32 v56, v56, v59
	v_cvt_pk_bf16_f32 v56, v56, v157
	ds_write_b16 v54, v56 offset:1120
	v_mov_b32_e32 v56, v145
	s_nop 0
	v_mov_b32_e32 v60, v57
	s_nop 0
	v_lshlrev_b32_e32 v56, 16, v56
	v_mul_f32_e32 v59, 0xbfb8aa3b, v56
	v_exp_f32_e32 v59, v59
	s_nop 0
	v_add_f32_e32 v59, 1.0, v59
	v_rcp_f32_e32 v59, v59
	s_nop 0
	v_mul_f32_e32 v56, v59, v56
	v_mul_f32_e32 v55, v55, v56
	v_cvt_pk_bf16_f32 v55, v55, v157
	v_pk_add_f32 v[58:59], v[60:61], v[68:69]
	ds_write_b16 v54, v55 offset:1152
	v_add_f32_e32 v55, v58, v59
	s_nop 1
	v_mov_b32_e32 v60, v69
	s_nop 0
	v_add_f32_dpp v55, v55, v55 quad_perm:[1,0,3,2] row_mask:0xf bank_mask:0xf
	s_nop 1
	s_nop 0
	v_add_f32_dpp v55, v55, v55 quad_perm:[2,3,0,1] row_mask:0xf bank_mask:0xf
	s_nop 1
	s_nop 0
	v_add_f32_dpp v55, v55, v55 row_half_mirror row_mask:0xf bank_mask:0xf
	s_nop 1
	s_nop 0
	v_add_f32_dpp v55, v55, v55 row_mirror row_mask:0xf bank_mask:0xf
	v_mul_f32_e32 v55, 0x3c800000, v55
	v_cndmask_b32_e32 v56, 0, v55, vcc
	v_pk_add_f32 v[58:59], v[64:65], v[56:57] op_sel_hi:[1,0] neg_lo:[0,1] neg_hi:[0,1]
	v_pk_add_f32 v[56:57], v[60:61], v[56:57] op_sel_hi:[1,0] neg_lo:[0,1] neg_hi:[0,1]
	v_pk_mul_f32 v[62:63], v[58:59], v[58:59]
	v_pk_mul_f32 v[60:61], v[56:57], v[56:57]
	v_add_f32_e32 v55, v62, v63
	v_add_f32_e32 v55, v61, v55
	v_add_f32_e32 v55, v60, v55
	s_nop 1
	v_lshlrev_b32_e32 v62, 16, v15
	v_and_b32_e32 v63, 0xffff0000, v15
	v_lshlrev_b32_e32 v64, 16, v16
	v_and_b32_e32 v65, 0xffff0000, v16
	s_nop 0
	v_add_f32_dpp v55, v55, v55 quad_perm:[1,0,3,2] row_mask:0xf bank_mask:0xf
	s_nop 1
	s_nop 0
	v_add_f32_dpp v55, v55, v55 quad_perm:[2,3,0,1] row_mask:0xf bank_mask:0xf
	s_nop 1
	s_nop 0
	v_add_f32_dpp v55, v55, v55 row_half_mirror row_mask:0xf bank_mask:0xf
	s_nop 1
	s_nop 0
	v_add_f32_dpp v55, v55, v55 row_mirror row_mask:0xf bank_mask:0xf
	v_fmamk_f32 v55, v55, 0x3c800000, v107
	v_cmp_gt_f32_e64 s[0:1], s3, v55
	v_mul_f32_e32 v60, 0x4b800000, v55
	s_nop 0
	v_cndmask_b32_e64 v55, v55, v60, s[0:1]
	v_rsq_f32_e32 v55, v55
	s_nop 0
	v_mul_f32_e32 v60, 0x45800000, v55
	v_cndmask_b32_e64 v55, v55, v60, s[0:1]
	v_mov_b32_e32 v60, v147
	s_nop 0
	v_mul_f32_e32 v58, v58, v55
	v_mul_f32_e32 v58, v106, v58
	v_mul_f32_e32 v59, v59, v55
	v_mul_f32_e32 v59, v103, v59
	s_nop 0
	v_lshlrev_b32_e32 v60, 16, v60
	v_mul_f32_e32 v61, 0xbfb8aa3b, v60
	v_exp_f32_e32 v61, v61
	v_mul_f32_e32 v57, v57, v55
	v_mul_f32_e32 v57, v101, v57
	v_mul_f32_e32 v55, v56, v55
	v_add_f32_e32 v61, 1.0, v61
	v_rcp_f32_e32 v61, v61
	v_mul_f32_e32 v55, v99, v55
	v_lshlrev_b32_e32 v56, 16, v18
	v_mul_f32_e32 v60, v61, v60
	v_mul_f32_e32 v58, v60, v58
	v_cvt_pk_bf16_f32 v58, v58, v157
	ds_write_b16 v54, v58 offset:1584
	v_mov_b32_e32 v58, v148
	s_nop 0
	v_and_b32_e32 v61, 0xffff0000, v14
	s_nop 0
	v_lshlrev_b32_e32 v58, 16, v58
	v_mul_f32_e32 v60, 0xbfb8aa3b, v58
	v_exp_f32_e32 v60, v60
	s_nop 0
	v_add_f32_e32 v60, 1.0, v60
	v_rcp_f32_e32 v60, v60
	s_nop 0
	v_mul_f32_e32 v58, v60, v58
	v_mul_f32_e32 v58, v58, v59
	v_cvt_pk_bf16_f32 v58, v58, v157
	ds_write_b16 v54, v58 offset:1616
	v_mov_b32_e32 v58, v149
	s_nop 0
	v_lshlrev_b32_e32 v60, 16, v14
	s_nop 0
	v_lshlrev_b32_e32 v58, 16, v58
	v_mul_f32_e32 v59, 0xbfb8aa3b, v58
	v_exp_f32_e32 v59, v59
	s_nop 0
	v_add_f32_e32 v59, 1.0, v59
	v_rcp_f32_e32 v59, v59
	s_nop 0
	v_mul_f32_e32 v58, v59, v58
	v_mul_f32_e32 v57, v58, v57
	v_cvt_pk_bf16_f32 v57, v57, v157
	ds_write_b16 v54, v57 offset:1648
	v_mov_b32_e32 v57, v150
	s_nop 0
	v_and_b32_e32 v59, 0xffff0000, v19
	s_nop 0
	v_lshlrev_b32_e32 v57, 16, v57
	v_mul_f32_e32 v58, 0xbfb8aa3b, v57
	v_exp_f32_e32 v58, v58
	s_nop 0
	v_add_f32_e32 v58, 1.0, v58
	v_rcp_f32_e32 v58, v58
	s_nop 0
	v_mul_f32_e32 v57, v58, v57
	v_mul_f32_e32 v55, v55, v57
	v_and_b32_e32 v57, 0xffff0000, v18
	v_lshlrev_b32_e32 v58, 16, v19
	v_lshlrev_b32_e32 v18, 16, v20
	v_and_b32_e32 v19, 0xffff0000, v20
	v_lshlrev_b32_e32 v20, 16, v21
	v_and_b32_e32 v21, 0xffff0000, v21
	v_mfma_f32_16x16x32_bf16 v[14:17], v[6:9], v[22:25], v[56:59]
	v_cvt_pk_bf16_f32 v55, v55, v157
	ds_write_b16 v54, v55 offset:1680
	v_mfma_f32_16x16x32_bf16 v[18:21], v[6:9], v[30:33], v[18:21]
	v_mfma_f32_16x16x32_bf16 v[22:25], v[10:13], v[34:37], v[18:21]
	v_mfma_f32_16x16x32_bf16 v[18:21], v[6:9], v[38:41], v[60:63]
	v_mfma_f32_16x16x32_bf16 v[6:9], v[6:9], v[46:49], v[64:67]
	v_mfma_f32_16x16x32_bf16 v[14:17], v[10:13], v[26:29], v[14:17]
	v_mfma_f32_16x16x32_bf16 v[18:21], v[10:13], v[42:45], v[18:21]
	v_mfma_f32_16x16x32_bf16 v[6:9], v[10:13], v[50:53], v[6:9]
	s_nop 5
	v_mov_b32_e32 v10, v14
	v_mov_b32_e32 v11, v18
	v_mov_b32_e32 v12, v22
	v_mov_b32_e32 v29, v18
	v_mov_b32_e32 v13, v6
	v_pk_add_f32 v[10:11], v[10:11], v[12:13]
	v_mov_b32_e32 v12, v14
	v_add_f32_e32 v10, v10, v11
	s_nop 1
	v_mov_b32_e32 v13, v22
	v_mov_b32_e32 v28, v6
	v_mov_b32_e32 v22, v15
	s_nop 0
	v_add_f32_dpp v10, v10, v10 quad_perm:[1,0,3,2] row_mask:0xf bank_mask:0xf
; #define LAS __attribute__((address_space(3)))
; __device__ __forceinline__ float bf2f(bf16_t b) { return __uint_as_float((unsigned)b << 16); }
; __device__ __forceinline__ bf16_t f2bf(float f) { return (bf16_t)(pk2(f, 0.f) & 0xffffu); }
; __device__ __forceinline__ float silu_acc(float x) { return x * frcp(1.0f + fexp(-x)); }
; __device__ __forceinline__ void mixer_out_phase(const Ctx& X, LAS unsigned char* lds, int layer, int tid, int wave, int lane) {
;     ...
; #pragma unroll
;             for (int j = 0; j < 4; ++j) {
;                 float sm = (acc[0][j] + acc[1][j]) + (acc[2][j] + acc[3][j]);
;                 sm += __shfl_xor(sm, 1); sm += __shfl_xor(sm, 2); sm += __shfl_xor(sm, 4); sm += __shfl_xor(sm, 8);
;                 const float mu = mixer == 0 ? sm * (1.f / 64.f) : 0.f;
;                 float d[4], s2 = 0.f;
; #pragma unroll
;                 for (int ct = 0; ct < 4; ++ct) { d[ct] = acc[ct][j] - mu; s2 += d[ct] * d[ct]; }
;                 s2 += __shfl_xor(s2, 1); s2 += __shfl_xor(s2, 2); s2 += __shfl_xor(s2, 4); s2 += __shfl_xor(s2, 8);
;                 const float rs = rsqrtf(s2 * (1.f / 64.f) + (mixer == 0 ? 1e-5f : 1e-6f));
;                 const int ii = 16 * (2 * half + rt) + 4 * q + j;
; #pragma unroll
;                 for (int ct = 0; ct < 4; ++ct) { LAS bf16_t* gp = GT + ii * GP + h * 64 + 16 * ct + r;
;                     const float y = d[ct] * rs * wv[ct] * silu_acc(bf2f(*gp));
;                     *gp = on ? f2bf(y) : (bf16_t)0; }
	s_nop 1
	s_nop 0
	v_add_f32_dpp v10, v10, v10 quad_perm:[2,3,0,1] row_mask:0xf bank_mask:0xf
	s_nop 1
	s_nop 0
	v_add_f32_dpp v10, v10, v10 row_half_mirror row_mask:0xf bank_mask:0xf
	s_nop 1
	s_nop 0
	v_add_f32_dpp v10, v10, v10 row_mirror row_mask:0xf bank_mask:0xf
	v_mul_f32_e32 v10, 0x3c800000, v10
	v_cndmask_b32_e32 v10, 0, v10, vcc
	v_pk_add_f32 v[12:13], v[12:13], v[10:11] op_sel_hi:[1,0] neg_lo:[0,1] neg_hi:[0,1]
	v_pk_add_f32 v[10:11], v[28:29], v[10:11] op_sel_hi:[1,0] neg_lo:[0,1] neg_hi:[0,1]
	v_pk_mul_f32 v[26:27], v[12:13], v[12:13]
	v_pk_mul_f32 v[28:29], v[10:11], v[10:11]
	v_add_f32_e32 v6, v26, v27
	v_add_f32_e32 v6, v29, v6
	v_add_f32_e32 v6, v28, v6
	s_nop 1
	s_nop 0
	v_add_f32_dpp v6, v6, v6 quad_perm:[1,0,3,2] row_mask:0xf bank_mask:0xf
	s_nop 1
	s_nop 0
	v_add_f32_dpp v6, v6, v6 quad_perm:[2,3,0,1] row_mask:0xf bank_mask:0xf
	s_nop 1
	s_nop 0
	v_add_f32_dpp v6, v6, v6 row_half_mirror row_mask:0xf bank_mask:0xf
	s_nop 1
	s_nop 0
	v_add_f32_dpp v6, v6, v6 row_mirror row_mask:0xf bank_mask:0xf
	v_fmamk_f32 v6, v6, 0x3c800000, v107
	v_cmp_gt_f32_e64 s[0:1], s3, v6
	v_mul_f32_e32 v14, 0x4b800000, v6
	s_nop 0
	v_cndmask_b32_e64 v6, v6, v14, s[0:1]
	v_rsq_f32_e32 v6, v6
	s_nop 0
	v_mul_f32_e32 v14, 0x45800000, v6
	v_cndmask_b32_e64 v6, v6, v14, s[0:1]
	v_mov_b32_e32 v14, v151
	s_nop 0
	v_mul_f32_e32 v12, v12, v6
	v_mul_f32_e32 v12, v106, v12
	v_mul_f32_e32 v13, v13, v6
	v_mul_f32_e32 v13, v103, v13
	s_nop 0
	v_lshlrev_b32_e32 v14, 16, v14
	v_mul_f32_e32 v18, 0xbfb8aa3b, v14
	v_exp_f32_e32 v18, v18
	v_mul_f32_e32 v11, v11, v6
	v_mul_f32_e32 v11, v101, v11
	v_mul_f32_e32 v6, v10, v6
	v_add_f32_e32 v18, 1.0, v18
	v_rcp_f32_e32 v18, v18
	v_mul_f32_e32 v6, v99, v6
	v_mul_f32_e32 v14, v18, v14
	v_mul_f32_e32 v12, v14, v12
	v_cvt_pk_bf16_f32 v12, v12, v157
	ds_write_b16 v54, v12 offset:8448
	v_mov_b32_e32 v12, v152
	s_nop 0
	v_mov_b32_e32 v18, v15
	s_nop 0
	v_lshlrev_b32_e32 v12, 16, v12
	v_mul_f32_e32 v14, 0xbfb8aa3b, v12
	v_exp_f32_e32 v14, v14
	s_nop 0
	v_add_f32_e32 v14, 1.0, v14
	v_rcp_f32_e32 v14, v14
	s_nop 0
	v_mul_f32_e32 v12, v14, v12
	v_mul_f32_e32 v12, v12, v13
	v_cvt_pk_bf16_f32 v12, v12, v157
	ds_write_b16 v54, v12 offset:8480
	v_mov_b32_e32 v12, v153
	s_nop 0
	s_nop 0
	v_lshlrev_b32_e32 v12, 16, v12
	v_mul_f32_e32 v13, 0xbfb8aa3b, v12
	v_exp_f32_e32 v13, v13
	s_nop 0
	v_add_f32_e32 v13, 1.0, v13
	v_rcp_f32_e32 v13, v13
	s_nop 0
	v_mul_f32_e32 v12, v13, v12
	v_mul_f32_e32 v11, v12, v11
	v_cvt_pk_bf16_f32 v11, v11, v157
	ds_write_b16 v54, v11 offset:8512
	v_mov_b32_e32 v11, v154
	s_nop 0
	s_nop 0
	v_lshlrev_b32_e32 v11, 16, v11
	v_mul_f32_e32 v12, 0xbfb8aa3b, v11
	v_exp_f32_e32 v12, v12
	s_nop 0
	v_add_f32_e32 v12, 1.0, v12
	v_rcp_f32_e32 v12, v12
	s_nop 0
	v_mul_f32_e32 v11, v12, v11
	v_mul_f32_e32 v6, v11, v6
	v_cvt_pk_bf16_f32 v6, v6, v157
	ds_write_b16 v54, v6 offset:8544
	v_mov_b32_e32 v6, v23
	v_pk_add_f32 v[10:11], v[18:19], v[6:7]
	v_mov_b32_e32 v18, v7
	v_add_f32_e32 v6, v10, v11
	s_nop 1
	s_nop 0
	v_add_f32_dpp v6, v6, v6 quad_perm:[1,0,3,2] row_mask:0xf bank_mask:0xf
	s_nop 1
	s_nop 0
	v_add_f32_dpp v6, v6, v6 quad_perm:[2,3,0,1] row_mask:0xf bank_mask:0xf
	s_nop 1
	s_nop 0
	v_add_f32_dpp v6, v6, v6 row_half_mirror row_mask:0xf bank_mask:0xf
	s_nop 1
	s_nop 0
	v_add_f32_dpp v6, v6, v6 row_mirror row_mask:0xf bank_mask:0xf
	v_mul_f32_e32 v6, 0x3c800000, v6
	v_cndmask_b32_e32 v6, 0, v6, vcc
	v_pk_add_f32 v[10:11], v[22:23], v[6:7] op_sel_hi:[1,0] neg_lo:[0,1] neg_hi:[0,1]
	v_pk_add_f32 v[6:7], v[18:19], v[6:7] op_sel_hi:[1,0] neg_lo:[0,1] neg_hi:[0,1]
	v_pk_mul_f32 v[12:13], v[10:11], v[10:11]
	v_pk_mul_f32 v[14:15], v[6:7], v[6:7]
	v_add_f32_e32 v12, v12, v13
	v_add_f32_e32 v12, v15, v12
	v_add_f32_e32 v12, v14, v12
	s_nop 1
	v_mov_b32_e32 v15, v20
	s_nop 0
	v_add_f32_dpp v12, v12, v12 quad_perm:[1,0,3,2] row_mask:0xf bank_mask:0xf
	s_nop 1
	s_nop 0
	v_add_f32_dpp v12, v12, v12 quad_perm:[2,3,0,1] row_mask:0xf bank_mask:0xf
	s_nop 1
	s_nop 0
	v_add_f32_dpp v12, v12, v12 row_half_mirror row_mask:0xf bank_mask:0xf
	s_nop 1
	s_nop 0
	v_add_f32_dpp v12, v12, v12 row_mirror row_mask:0xf bank_mask:0xf
	v_fmamk_f32 v12, v12, 0x3c800000, v107
	v_cmp_gt_f32_e64 s[0:1], s3, v12
	v_mul_f32_e32 v13, 0x4b800000, v12
	s_nop 0
	v_cndmask_b32_e64 v12, v12, v13, s[0:1]
	v_rsq_f32_e32 v12, v12
	s_nop 0
	v_mul_f32_e32 v13, 0x45800000, v12
	v_cndmask_b32_e64 v12, v12, v13, s[0:1]
	v_mov_b32_e32 v13, v155
	s_nop 0
	v_mul_f32_e32 v10, v10, v12
	v_mul_f32_e32 v10, v106, v10
	v_mul_f32_e32 v11, v11, v12
	v_mul_f32_e32 v11, v103, v11
	s_nop 0
	v_lshlrev_b32_e32 v13, 16, v13
	v_mul_f32_e32 v14, 0xbfb8aa3b, v13
	v_exp_f32_e32 v14, v14
	v_mul_f32_e32 v7, v7, v12
	v_mul_f32_e32 v7, v101, v7
	v_mul_f32_e32 v6, v6, v12
	v_add_f32_e32 v14, 1.0, v14
	v_rcp_f32_e32 v14, v14
	v_mul_f32_e32 v6, v99, v6
	v_mul_f32_e32 v13, v14, v13
	v_mul_f32_e32 v10, v13, v10
	v_cvt_pk_bf16_f32 v10, v10, v157
	ds_write_b16 v54, v10 offset:8976
	v_mov_b32_e32 v10, v182
	s_nop 0
	v_mov_b32_e32 v14, v8
	s_nop 0
	v_lshlrev_b32_e32 v10, 16, v10
	v_mul_f32_e32 v13, 0xbfb8aa3b, v10
	v_exp_f32_e32 v13, v13
	s_nop 0
	v_add_f32_e32 v13, 1.0, v13
	v_rcp_f32_e32 v13, v13
	s_nop 0
	v_mul_f32_e32 v10, v13, v10
	v_mul_f32_e32 v10, v10, v11
	v_cvt_pk_bf16_f32 v10, v10, v157
	ds_write_b16 v54, v10 offset:9008
	v_mov_b32_e32 v10, v183
	s_nop 0
	s_nop 0
	v_lshlrev_b32_e32 v10, 16, v10
	v_mul_f32_e32 v11, 0xbfb8aa3b, v10
	v_exp_f32_e32 v11, v11
	s_nop 0
	v_add_f32_e32 v11, 1.0, v11
	v_rcp_f32_e32 v11, v11
	s_nop 0
	v_mul_f32_e32 v10, v11, v10
	v_mul_f32_e32 v7, v10, v7
	v_cvt_pk_bf16_f32 v7, v7, v157
	ds_write_b16 v54, v7 offset:9040
	v_mov_b32_e32 v7, v184
	s_nop 0
; #define LAS __attribute__((address_space(3)))
; __device__ __forceinline__ float bf2f(bf16_t b) { return __uint_as_float((unsigned)b << 16); }
; __device__ __forceinline__ bf16_t f2bf(float f) { return (bf16_t)(pk2(f, 0.f) & 0xffffu); }
; __device__ __forceinline__ float silu_acc(float x) { return x * frcp(1.0f + fexp(-x)); }
; __device__ __forceinline__ void mixer_out_phase(const Ctx& X, LAS unsigned char* lds, int layer, int tid, int wave, int lane) {
;     ...
; #pragma unroll
;             for (int j = 0; j < 4; ++j) {
;                 float sm = (acc[0][j] + acc[1][j]) + (acc[2][j] + acc[3][j]);
;                 sm += __shfl_xor(sm, 1); sm += __shfl_xor(sm, 2); sm += __shfl_xor(sm, 4); sm += __shfl_xor(sm, 8);
;                 const float mu = mixer == 0 ? sm * (1.f / 64.f) : 0.f;
;                 float d[4], s2 = 0.f;
; #pragma unroll
;                 for (int ct = 0; ct < 4; ++ct) { d[ct] = acc[ct][j] - mu; s2 += d[ct] * d[ct]; }
;                 s2 += __shfl_xor(s2, 1); s2 += __shfl_xor(s2, 2); s2 += __shfl_xor(s2, 4); s2 += __shfl_xor(s2, 8);
;                 const float rs = rsqrtf(s2 * (1.f / 64.f) + (mixer == 0 ? 1e-5f : 1e-6f));
;                 const int ii = 16 * (2 * half + rt) + 4 * q + j;
; #pragma unroll
;                 for (int ct = 0; ct < 4; ++ct) { LAS bf16_t* gp = GT + ii * GP + h * 64 + 16 * ct + r;
;                     const float y = d[ct] * rs * wv[ct] * silu_acc(bf2f(*gp));
;                     *gp = on ? f2bf(y) : (bf16_t)0; }
	v_mov_b32_e32 v11, v8
	s_nop 0
	v_lshlrev_b32_e32 v7, 16, v7
	v_mul_f32_e32 v10, 0xbfb8aa3b, v7
	v_exp_f32_e32 v10, v10
	s_nop 0
	v_add_f32_e32 v10, 1.0, v10
	v_rcp_f32_e32 v10, v10
	s_nop 0
	v_mul_f32_e32 v7, v10, v7
	v_mul_f32_e32 v6, v6, v7
	v_cvt_pk_bf16_f32 v6, v6, v157
	ds_write_b16 v54, v6 offset:9072
	v_mov_b32_e32 v6, v16
	v_mov_b32_e32 v7, v20
	v_mov_b32_e32 v10, v24
	v_pk_add_f32 v[6:7], v[6:7], v[10:11]
	v_mov_b32_e32 v10, v16
	v_add_f32_e32 v6, v6, v7
	s_nop 1
	v_mov_b32_e32 v11, v24
	v_mov_b32_e32 v20, v17
	v_mov_b32_e32 v24, v17
	s_nop 0
	v_add_f32_dpp v6, v6, v6 quad_perm:[1,0,3,2] row_mask:0xf bank_mask:0xf
	s_nop 1
	s_nop 0
	v_add_f32_dpp v6, v6, v6 quad_perm:[2,3,0,1] row_mask:0xf bank_mask:0xf
	s_nop 1
	s_nop 0
	v_add_f32_dpp v6, v6, v6 row_half_mirror row_mask:0xf bank_mask:0xf
	s_nop 1
	s_nop 0
	v_add_f32_dpp v6, v6, v6 row_mirror row_mask:0xf bank_mask:0xf
	v_mul_f32_e32 v6, 0x3c800000, v6
	v_cndmask_b32_e32 v6, 0, v6, vcc
	v_pk_add_f32 v[10:11], v[10:11], v[6:7] op_sel_hi:[1,0] neg_lo:[0,1] neg_hi:[0,1]
	v_pk_add_f32 v[6:7], v[14:15], v[6:7] op_sel_hi:[1,0] neg_lo:[0,1] neg_hi:[0,1]
	v_pk_mul_f32 v[12:13], v[10:11], v[10:11]
	v_pk_mul_f32 v[14:15], v[6:7], v[6:7]
	v_add_f32_e32 v8, v12, v13
	v_add_f32_e32 v8, v15, v8
	v_add_f32_e32 v8, v14, v8
	s_nop 1
	s_nop 0
	v_add_f32_dpp v8, v8, v8 quad_perm:[1,0,3,2] row_mask:0xf bank_mask:0xf
	s_nop 1
	s_nop 0
	v_add_f32_dpp v8, v8, v8 quad_perm:[2,3,0,1] row_mask:0xf bank_mask:0xf
	s_nop 1
	s_nop 0
	v_add_f32_dpp v8, v8, v8 row_half_mirror row_mask:0xf bank_mask:0xf
	s_nop 1
	s_nop 0
	v_add_f32_dpp v8, v8, v8 row_mirror row_mask:0xf bank_mask:0xf
	v_fmamk_f32 v8, v8, 0x3c800000, v107
	v_cmp_gt_f32_e64 s[0:1], s3, v8
	v_mul_f32_e32 v12, 0x4b800000, v8
	s_nop 0
	v_cndmask_b32_e64 v8, v8, v12, s[0:1]
	v_rsq_f32_e32 v8, v8
	s_nop 0
	v_mul_f32_e32 v12, 0x45800000, v8
	v_cndmask_b32_e64 v8, v8, v12, s[0:1]
	v_mov_b32_e32 v12, v185
	s_nop 0
	v_mul_f32_e32 v10, v10, v8
	v_mul_f32_e32 v10, v106, v10
	v_mul_f32_e32 v11, v11, v8
	v_mul_f32_e32 v11, v103, v11
	s_nop 0
	v_lshlrev_b32_e32 v12, 16, v12
	v_mul_f32_e32 v13, 0xbfb8aa3b, v12
	v_exp_f32_e32 v13, v13
	v_mul_f32_e32 v7, v7, v8
	v_mul_f32_e32 v7, v101, v7
	v_mul_f32_e32 v6, v6, v8
	v_add_f32_e32 v13, 1.0, v13
	v_rcp_f32_e32 v13, v13
	v_mul_f32_e32 v6, v99, v6
	v_mov_b32_e32 v8, v25
	s_lshl_b32 s0, s11, 1
	v_mul_f32_e32 v12, v13, v12
	v_mul_f32_e32 v10, v12, v10
	v_cvt_pk_bf16_f32 v10, v10, v157
	ds_write_b16 v54, v10 offset:9504
	v_mov_b32_e32 v10, v186
	s_nop 0
	s_add_u32 s0, s60, s0
	s_addc_u32 s1, s67, 0
	s_add_i32 s10, s10, s18
	s_cmpk_lt_i32 s10, 0x600
	s_nop 0
	v_lshlrev_b32_e32 v10, 16, v10
	v_mul_f32_e32 v12, 0xbfb8aa3b, v10
	v_exp_f32_e32 v12, v12
	s_nop 0
	v_add_f32_e32 v12, 1.0, v12
	v_rcp_f32_e32 v12, v12
	s_nop 0
	v_mul_f32_e32 v10, v12, v10
	v_mul_f32_e32 v10, v10, v11
	v_cvt_pk_bf16_f32 v10, v10, v157
	ds_write_b16 v54, v10 offset:9536
	v_mov_b32_e32 v10, v187
	s_nop 0
	s_nop 0
	v_lshlrev_b32_e32 v10, 16, v10
	v_mul_f32_e32 v11, 0xbfb8aa3b, v10
	v_exp_f32_e32 v11, v11
	s_nop 0
	v_add_f32_e32 v11, 1.0, v11
	v_rcp_f32_e32 v11, v11
	s_nop 0
	v_mul_f32_e32 v10, v11, v10
	v_mul_f32_e32 v7, v10, v7
	v_cvt_pk_bf16_f32 v7, v7, v157
	ds_write_b16 v54, v7 offset:9568
	v_mov_b32_e32 v7, v188
	s_nop 0
	s_nop 0
	v_lshlrev_b32_e32 v7, 16, v7
	v_mul_f32_e32 v10, 0xbfb8aa3b, v7
	v_exp_f32_e32 v10, v10
	s_nop 0
	v_add_f32_e32 v10, 1.0, v10
	v_rcp_f32_e32 v10, v10
	s_nop 0
	v_mul_f32_e32 v7, v10, v7
	v_mul_f32_e32 v6, v6, v7
	v_cvt_pk_bf16_f32 v6, v6, v157
	ds_write_b16 v54, v6 offset:9600
	v_pk_add_f32 v[6:7], v[20:21], v[8:9]
	v_mov_b32_e32 v20, v9
	v_add_f32_e32 v6, v6, v7
	s_nop 1
	s_nop 0
	v_add_f32_dpp v6, v6, v6 quad_perm:[1,0,3,2] row_mask:0xf bank_mask:0xf
	s_nop 1
	s_nop 0
	v_add_f32_dpp v6, v6, v6 quad_perm:[2,3,0,1] row_mask:0xf bank_mask:0xf
	s_nop 1
	s_nop 0
	v_add_f32_dpp v6, v6, v6 row_half_mirror row_mask:0xf bank_mask:0xf
	s_nop 1
	s_nop 0
	v_add_f32_dpp v6, v6, v6 row_mirror row_mask:0xf bank_mask:0xf
	v_mul_f32_e32 v6, 0x3c800000, v6
	v_cndmask_b32_e32 v6, 0, v6, vcc
	v_pk_add_f32 v[10:11], v[24:25], v[6:7] op_sel_hi:[1,0] neg_lo:[0,1] neg_hi:[0,1]
	v_pk_add_f32 v[6:7], v[20:21], v[6:7] op_sel_hi:[1,0] neg_lo:[0,1] neg_hi:[0,1]
	v_pk_mul_f32 v[12:13], v[10:11], v[10:11]
	v_pk_mul_f32 v[8:9], v[6:7], v[6:7]
	v_add_f32_e32 v12, v12, v13
	v_add_f32_e32 v9, v9, v12
	v_add_f32_e32 v8, v8, v9
	s_nop 1
	s_nop 0
	v_add_f32_dpp v8, v8, v8 quad_perm:[1,0,3,2] row_mask:0xf bank_mask:0xf
	s_nop 1
	s_nop 0
	v_add_f32_dpp v8, v8, v8 quad_perm:[2,3,0,1] row_mask:0xf bank_mask:0xf
	s_nop 1
	s_nop 0
	v_add_f32_dpp v8, v8, v8 row_half_mirror row_mask:0xf bank_mask:0xf
	s_nop 1
	s_nop 0
	v_add_f32_dpp v8, v8, v8 row_mirror row_mask:0xf bank_mask:0xf
	v_fmac_f32_e32 v107, 0x3c800000, v8
	v_cmp_gt_f32_e32 vcc, s3, v107
	v_mul_f32_e32 v8, 0x4b800000, v107
	s_nop 0
	v_cndmask_b32_e32 v8, v107, v8, vcc
	v_rsq_f32_e32 v8, v8
	s_nop 0
	v_mul_f32_e32 v9, 0x45800000, v8
	v_cndmask_b32_e32 v8, v8, v9, vcc
	v_mov_b32_e32 v9, v189
	s_nop 0
	v_mul_f32_e32 v10, v10, v8
	v_mul_f32_e32 v10, v106, v10
	v_mul_f32_e32 v7, v7, v8
	v_mul_f32_e32 v7, v101, v7
	s_nop 0
	v_lshlrev_b32_e32 v9, 16, v9
	v_mul_f32_e32 v12, 0xbfb8aa3b, v9
	v_exp_f32_e32 v12, v12
	v_mul_f32_e32 v6, v6, v8
	v_mul_f32_e32 v6, v99, v6
	v_add_f32_e32 v12, 1.0, v12
	v_rcp_f32_e32 v12, v12
	s_nop 0
	v_mul_f32_e32 v9, v12, v9
	v_mul_f32_e32 v9, v9, v10
	v_cvt_pk_bf16_f32 v9, v9, v157
	ds_write_b16 v54, v9 offset:10032
	v_mov_b32_e32 v9, v190
	s_nop 0
	v_lshlrev_b64 v[12:13], 11, v[92:93]
	s_nop 0
	v_lshlrev_b32_e32 v9, 16, v9
	v_mul_f32_e32 v10, 0xbfb8aa3b, v9
	v_exp_f32_e32 v10, v10
	s_nop 0
	v_add_f32_e32 v10, 1.0, v10
	v_rcp_f32_e32 v10, v10
	s_nop 0
	v_mul_f32_e32 v9, v10, v9
	v_mul_f32_e32 v10, v11, v8
	v_mul_f32_e32 v10, v103, v10
	v_mul_f32_e32 v9, v9, v10
	v_cvt_pk_bf16_f32 v9, v9, v157
	ds_write_b16 v54, v9 offset:10064
	v_mov_b32_e32 v9, v191
	s_nop 0
	s_nop 0
	v_lshlrev_b32_e32 v9, 16, v9
	v_mul_f32_e32 v10, 0xbfb8aa3b, v9
	v_exp_f32_e32 v10, v10
	s_nop 0
	v_add_f32_e32 v10, 1.0, v10
	v_rcp_f32_e32 v10, v10
	s_nop 0
	v_mul_f32_e32 v9, v10, v9
	v_mul_f32_e32 v7, v9, v7
	v_cvt_pk_bf16_f32 v7, v7, v157
	ds_write_b16 v54, v7 offset:10096
	v_mov_b32_e32 v7, v192
	s_nop 0
	v_lshl_add_u64 v[10:11], s[0:1], 0, v[156:157]
	v_lshl_add_u64 v[12:13], v[10:11], 0, v[12:13]
	s_nop 0
	v_lshlrev_b32_e32 v7, 16, v7
	v_mul_f32_e32 v9, 0xbfb8aa3b, v7
	v_exp_f32_e32 v9, v9
	s_nop 0
	v_add_f32_e32 v9, 1.0, v9
	v_rcp_f32_e32 v9, v9
	s_nop 0
	v_mul_f32_e32 v7, v9, v7
	v_mul_f32_e32 v6, v6, v7
	v_cvt_pk_bf16_f32 v6, v6, v157
	ds_write_b16 v54, v6 offset:10128
	s_waitcnt lgkmcnt(0)
	s_barrier
; #define LAS __attribute__((address_space(3)))
; #define LBAR() do { asm volatile("s_waitcnt lgkmcnt(0)" ::: "memory"); __builtin_amdgcn_s_barrier(); asm volatile("" ::: "memory"); } while (0)
; __device__ __forceinline__ void mixer_out_phase(const Ctx& X, LAS unsigned char* lds, int layer, int tid, int wave, int lane) {
;     ...
;         LBAR();
; #pragma unroll
;         for (int n = 0; n < 4; ++n) { const int idx = tid + 512 * n; __builtin_nontemporal_store(*(const LAS u32x4*)(GT + (idx >> 5) * GP + (idx & 31) * 8), (u32x4*)(mix + (row0 + (idx >> 5)) * D + moff + (idx & 31) * 8)); }
;         LBAR();
;     }
	ds_read_b128 v[6:9], v96
	s_waitcnt lgkmcnt(0)
	global_store_dwordx4 v[12:13], v[6:9], off nt
	ds_read_b128 v[6:9], v94
	v_lshlrev_b64 v[12:13], 11, v[90:91]
	v_lshl_add_u64 v[12:13], v[10:11], 0, v[12:13]
	s_waitcnt lgkmcnt(0)
	global_store_dwordx4 v[12:13], v[6:9], off nt
	ds_read_b128 v[6:9], v76
	v_lshlrev_b64 v[12:13], 11, v[88:89]
	v_lshl_add_u64 v[12:13], v[10:11], 0, v[12:13]
	s_waitcnt lgkmcnt(0)
	global_store_dwordx4 v[12:13], v[6:9], off nt
	ds_read_b128 v[6:9], v74
	v_lshlrev_b64 v[12:13], 11, v[86:87]
	v_lshl_add_u64 v[10:11], v[10:11], 0, v[12:13]
	s_waitcnt lgkmcnt(0)
	global_store_dwordx4 v[10:11], v[6:9], off nt
	s_waitcnt lgkmcnt(0)
	s_barrier
	s_cbranch_scc1 .LBB0_888
	v_readlane_b32 s54, v255, 7
	v_readlane_b32 s56, v255, 9
	v_readlane_b32 s58, v255, 11
	v_readlane_b32 s48, v255, 13
	v_readlane_b32 s50, v255, 15
	v_readlane_b32 s52, v255, 17
	v_readlane_b32 s55, v255, 8
	v_readlane_b32 s57, v255, 10
	v_readlane_b32 s59, v255, 12
	v_readlane_b32 s49, v255, 14
	v_readlane_b32 s51, v255, 16
	v_readlane_b32 s53, v255, 18
	s_mov_b64 s[22:23], s[64:65]
	v_readlane_b32 s19, v255, 26
